# GEMM K-loops: first iteration peeled with src C = 0 on each accumulator's first MFMA; the 128 v_mov accumulator zero-inits per unit removed
# speedup vs baseline: 1.0139x; 1.0047x over previous
.LBB0_245:
	s_ashr_i32 s61, s60, 31
	s_xor_b64 s[76:77], s[40:41], -1
	s_lshl_b64 s[2:3], s[60:61], 19
	s_add_u32 s62, s86, s2
	s_addc_u32 s63, s87, s3
	s_and_b64 s[2:3], s[40:41], exec
	s_cselect_b32 s1, s63, s19
	s_cselect_b32 s2, s62, s18
	s_ashr_i32 s59, s58, 31
	s_lshl_b64 s[4:5], s[58:59], 19
	s_add_u32 s92, s28, s4
	s_addc_u32 s93, s29, s5
	s_and_b64 s[4:5], s[40:41], exec
	s_cselect_b32 s3, s93, s7
	s_cselect_b32 s4, s92, s6
	s_add_u32 s40, s18, 0x40080
	s_addc_u32 s41, s19, 0
	s_add_u32 s5, s6, 0x100
	s_addc_u32 s17, s7, 0
	s_mov_b32 s20, -2
	s_add_u32 s6, s40, 0xfffc0080
	s_addc_u32 s7, s41, -1
	s_add_i32 s21, s69, 0x100
	v_add_u32_e32 v0, s21, v151
	ds_read_b128 v[158:161], v0
	ds_read_b128 v[162:165], v0 offset:1024
	ds_read_b128 v[174:177], v0 offset:2048
	ds_read_b128 v[178:181], v0 offset:3072
	s_cmp_eq_u32 s20, 12
	s_cselect_b32 s19, s1, s7
	s_cselect_b32 s18, s2, s6
	s_cselect_b32 s7, s3, s17
	s_cselect_b32 s6, s4, s5
	v_lshl_add_u64 v[226:227], s[40:41], 0, v[154:155]
	s_add_i32 m0, s11, 0xc000
	ds_read_b128 v[182:185], v172
	ds_read_b128 v[186:189], v172 offset:1024
	ds_read_b128 v[190:193], v172 offset:2048
	ds_read_b128 v[206:209], v172 offset:3072
	ds_read_b128 v[210:213], v172 offset:4096
	ds_read_b128 v[214:217], v172 offset:5120
	ds_read_b128 v[218:221], v172 offset:6144
	ds_read_b128 v[222:225], v172 offset:7168
	global_load_lds_dwordx4 v[226:227], off
	v_lshl_add_u64 v[226:227], s[40:41], 0, v[156:157]
	s_add_i32 m0, s11, 0xe000
	s_nop 0
	global_load_lds_dwordx4 v[226:227], off
	s_waitcnt lgkmcnt(8)
	s_barrier
	s_waitcnt lgkmcnt(0)
	s_setprio 1
	s_waitcnt lgkmcnt(0)
	v_mfma_f32_16x16x32_bf16 v[126:129], v[158:161], v[182:185], 0
	v_mfma_f32_16x16x32_bf16 v[122:125], v[174:177], v[182:185], 0
	v_mfma_f32_16x16x32_bf16 v[110:113], v[158:161], v[190:193], 0
	v_mfma_f32_16x16x32_bf16 v[106:109], v[174:177], v[190:193], 0
	v_mfma_f32_16x16x32_bf16 v[94:97], v[158:161], v[210:213], 0
	v_mfma_f32_16x16x32_bf16 v[90:93], v[174:177], v[210:213], 0
	v_mfma_f32_16x16x32_bf16 v[78:81], v[158:161], v[218:221], 0
	v_mfma_f32_16x16x32_bf16 v[74:77], v[174:177], v[218:221], 0
	v_mfma_f32_16x16x32_bf16 v[126:129], v[162:165], v[186:189], v[126:129]
	v_mfma_f32_16x16x32_bf16 v[122:125], v[178:181], v[186:189], v[122:125]
	v_mfma_f32_16x16x32_bf16 v[110:113], v[162:165], v[206:209], v[110:113]
	v_mfma_f32_16x16x32_bf16 v[106:109], v[178:181], v[206:209], v[106:109]
	v_mfma_f32_16x16x32_bf16 v[94:97], v[162:165], v[214:217], v[94:97]
	v_mfma_f32_16x16x32_bf16 v[90:93], v[178:181], v[214:217], v[90:93]
	v_mfma_f32_16x16x32_bf16 v[78:81], v[162:165], v[222:225], v[78:81]
	v_mfma_f32_16x16x32_bf16 v[74:77], v[178:181], v[222:225], v[74:77]
	s_setprio 0
	s_barrier
	s_add_i32 s24, s96, 0x100
	s_add_i32 s21, s21, s10
	v_add_u32_e32 v0, s24, v151
	v_lshl_add_u64 v[242:243], s[6:7], 0, v[132:133]
	s_mov_b32 m0, s21
	ds_read_b128 v[226:229], v0
	ds_read_b128 v[230:233], v0 offset:1024
	ds_read_b128 v[234:237], v0 offset:2048
	ds_read_b128 v[238:241], v0 offset:3072
	global_load_lds_dwordx4 v[242:243], off
	v_lshl_add_u64 v[244:245], s[6:7], 0, v[136:137]
	s_add_i32 m0, s21, 0x2000
	s_nop 0
	global_load_lds_dwordx4 v[244:245], off
	s_barrier
	s_waitcnt lgkmcnt(0)
	s_setprio 1
	s_waitcnt lgkmcnt(0)
	v_mfma_f32_16x16x32_bf16 v[118:121], v[226:229], v[182:185], 0
	v_mfma_f32_16x16x32_bf16 v[114:117], v[234:237], v[182:185], 0
	v_mfma_f32_16x16x32_bf16 v[102:105], v[226:229], v[190:193], 0
	v_mfma_f32_16x16x32_bf16 v[98:101], v[234:237], v[190:193], 0
	v_mfma_f32_16x16x32_bf16 v[86:89], v[226:229], v[210:213], 0
	v_mfma_f32_16x16x32_bf16 v[82:85], v[234:237], v[210:213], 0
	v_mfma_f32_16x16x32_bf16 v[70:73], v[226:229], v[218:221], 0
	v_mfma_f32_16x16x32_bf16 v[66:69], v[234:237], v[218:221], 0
	v_mfma_f32_16x16x32_bf16 v[118:121], v[230:233], v[186:189], v[118:121]
	v_mfma_f32_16x16x32_bf16 v[114:117], v[238:241], v[186:189], v[114:117]
	v_mfma_f32_16x16x32_bf16 v[102:105], v[230:233], v[206:209], v[102:105]
	v_mfma_f32_16x16x32_bf16 v[98:101], v[238:241], v[206:209], v[98:101]
	v_mfma_f32_16x16x32_bf16 v[86:89], v[230:233], v[214:217], v[86:89]
	v_mfma_f32_16x16x32_bf16 v[82:85], v[238:241], v[214:217], v[82:85]
	v_mfma_f32_16x16x32_bf16 v[70:73], v[230:233], v[222:225], v[70:73]
	v_mfma_f32_16x16x32_bf16 v[66:69], v[238:241], v[222:225], v[66:69]
	s_setprio 0
	s_mov_b32 m0, s11
	v_lshl_add_u64 v[246:247], s[18:19], 0, v[130:131]
	s_barrier
	ds_read_b128 v[182:185], v172 offset:16384
	ds_read_b128 v[186:189], v172 offset:17408
	ds_read_b128 v[190:193], v172 offset:18432
	ds_read_b128 v[206:209], v172 offset:19456
	ds_read_b128 v[210:213], v172 offset:20480
	ds_read_b128 v[214:217], v172 offset:21504
	ds_read_b128 v[218:221], v172 offset:22528
	ds_read_b128 v[222:225], v172 offset:23552
	global_load_lds_dwordx4 v[246:247], off
	v_lshl_add_u64 v[248:249], s[18:19], 0, v[134:135]
	s_mov_b32 m0, s12
	s_nop 0
	global_load_lds_dwordx4 v[248:249], off
	s_barrier
	s_waitcnt lgkmcnt(0)
	s_setprio 1
	s_waitcnt lgkmcnt(0)
	v_mfma_f32_16x16x32_bf16 v[62:65], v[158:161], v[182:185], 0
	v_mfma_f32_16x16x32_bf16 v[58:61], v[174:177], v[182:185], 0
	v_mfma_f32_16x16x32_bf16 v[46:49], v[158:161], v[190:193], 0
	v_mfma_f32_16x16x32_bf16 v[42:45], v[174:177], v[190:193], 0
	v_mfma_f32_16x16x32_bf16 v[30:33], v[158:161], v[210:213], 0
	v_mfma_f32_16x16x32_bf16 v[26:29], v[174:177], v[210:213], 0
	v_mfma_f32_16x16x32_bf16 v[14:17], v[158:161], v[218:221], 0
	v_mfma_f32_16x16x32_bf16 v[10:13], v[174:177], v[218:221], 0
	v_mfma_f32_16x16x32_bf16 v[62:65], v[162:165], v[186:189], v[62:65]
	v_mfma_f32_16x16x32_bf16 v[58:61], v[178:181], v[186:189], v[58:61]
	v_mfma_f32_16x16x32_bf16 v[46:49], v[162:165], v[206:209], v[46:49]
	v_mfma_f32_16x16x32_bf16 v[42:45], v[178:181], v[206:209], v[42:45]
	v_mfma_f32_16x16x32_bf16 v[30:33], v[162:165], v[214:217], v[30:33]
	v_mfma_f32_16x16x32_bf16 v[26:29], v[178:181], v[214:217], v[26:29]
	v_mfma_f32_16x16x32_bf16 v[14:17], v[162:165], v[222:225], v[14:17]
	v_mfma_f32_16x16x32_bf16 v[10:13], v[178:181], v[222:225], v[10:13]
	s_setprio 0
	s_barrier
	s_add_u32 s22, s6, 0x40000
	s_addc_u32 s23, s7, 0
	s_add_i32 s21, s24, s10
	v_lshl_add_u64 v[158:159], s[22:23], 0, v[132:133]
	s_mov_b32 m0, s21
	s_nop 0
	global_load_lds_dwordx4 v[158:159], off
	v_lshl_add_u64 v[158:159], s[22:23], 0, v[136:137]
	s_add_i32 m0, s21, 0x2000
	s_nop 0
	global_load_lds_dwordx4 v[158:159], off
	s_waitcnt vmcnt(6)
	s_barrier
	s_setprio 1
	v_mfma_f32_16x16x32_bf16 v[54:57], v[226:229], v[182:185], 0
	v_mfma_f32_16x16x32_bf16 v[50:53], v[234:237], v[182:185], 0
	v_mfma_f32_16x16x32_bf16 v[38:41], v[226:229], v[190:193], 0
	v_mfma_f32_16x16x32_bf16 v[34:37], v[234:237], v[190:193], 0
	v_mfma_f32_16x16x32_bf16 v[22:25], v[226:229], v[210:213], 0
	v_mfma_f32_16x16x32_bf16 v[18:21], v[234:237], v[210:213], 0
	v_mfma_f32_16x16x32_bf16 v[6:9], v[226:229], v[218:221], 0
	v_mfma_f32_16x16x32_bf16 v[2:5], v[234:237], v[218:221], 0
	v_mfma_f32_16x16x32_bf16 v[54:57], v[230:233], v[186:189], v[54:57]
	v_mfma_f32_16x16x32_bf16 v[50:53], v[238:241], v[186:189], v[50:53]
	v_mfma_f32_16x16x32_bf16 v[38:41], v[230:233], v[206:209], v[38:41]
	v_mfma_f32_16x16x32_bf16 v[34:37], v[238:241], v[206:209], v[34:37]
	v_mfma_f32_16x16x32_bf16 v[22:25], v[230:233], v[214:217], v[22:25]
	v_mfma_f32_16x16x32_bf16 v[18:21], v[238:241], v[214:217], v[18:21]
	v_mfma_f32_16x16x32_bf16 v[6:9], v[230:233], v[222:225], v[6:9]
	v_mfma_f32_16x16x32_bf16 v[2:5], v[238:241], v[222:225], v[2:5]
	s_setprio 0
	s_add_i32 s21, s97, 0x100
	v_add_u32_e32 v0, s21, v151
	s_barrier
	ds_read_b128 v[158:161], v0
	ds_read_b128 v[162:165], v0 offset:1024
	ds_read_b128 v[174:177], v0 offset:2048
	ds_read_b128 v[178:181], v0 offset:3072
	s_add_u32 s18, s18, 0x40000
	s_addc_u32 s19, s19, 0
	s_mov_b32 m0, s13
	v_lshl_add_u64 v[226:227], s[18:19], 0, v[130:131]
	ds_read_b128 v[182:185], v172 offset:32768
	ds_read_b128 v[186:189], v172 offset:33792
	ds_read_b128 v[190:193], v172 offset:34816
	ds_read_b128 v[206:209], v172 offset:35840
	ds_read_b128 v[210:213], v172 offset:36864
	ds_read_b128 v[214:217], v172 offset:37888
	ds_read_b128 v[218:221], v172 offset:38912
	ds_read_b128 v[222:225], v172 offset:39936
	global_load_lds_dwordx4 v[226:227], off
	v_lshl_add_u64 v[226:227], s[18:19], 0, v[134:135]
	s_mov_b32 m0, s45
	s_nop 0
	global_load_lds_dwordx4 v[226:227], off
	s_waitcnt lgkmcnt(8)
	s_barrier
	s_waitcnt lgkmcnt(0)
	s_setprio 1
	s_waitcnt lgkmcnt(0)
	v_mfma_f32_16x16x32_bf16 v[126:129], v[158:161], v[182:185], v[126:129]
	v_mfma_f32_16x16x32_bf16 v[122:125], v[174:177], v[182:185], v[122:125]
	v_mfma_f32_16x16x32_bf16 v[110:113], v[158:161], v[190:193], v[110:113]
	v_mfma_f32_16x16x32_bf16 v[106:109], v[174:177], v[190:193], v[106:109]
	v_mfma_f32_16x16x32_bf16 v[94:97], v[158:161], v[210:213], v[94:97]
	v_mfma_f32_16x16x32_bf16 v[90:93], v[174:177], v[210:213], v[90:93]
	v_mfma_f32_16x16x32_bf16 v[78:81], v[158:161], v[218:221], v[78:81]
	v_mfma_f32_16x16x32_bf16 v[74:77], v[174:177], v[218:221], v[74:77]
	v_mfma_f32_16x16x32_bf16 v[126:129], v[162:165], v[186:189], v[126:129]
	v_mfma_f32_16x16x32_bf16 v[122:125], v[178:181], v[186:189], v[122:125]
	v_mfma_f32_16x16x32_bf16 v[110:113], v[162:165], v[206:209], v[110:113]
	v_mfma_f32_16x16x32_bf16 v[106:109], v[178:181], v[206:209], v[106:109]
	v_mfma_f32_16x16x32_bf16 v[94:97], v[162:165], v[214:217], v[94:97]
	v_mfma_f32_16x16x32_bf16 v[90:93], v[178:181], v[214:217], v[90:93]
	v_mfma_f32_16x16x32_bf16 v[78:81], v[162:165], v[222:225], v[78:81]
	v_mfma_f32_16x16x32_bf16 v[74:77], v[178:181], v[222:225], v[74:77]
	s_setprio 0
	s_barrier
	s_add_i32 s18, s44, 0x100
	s_add_i32 s19, s21, s10
	v_add_u32_e32 v0, s18, v151
	v_lshl_add_u64 v[242:243], v[242:243], 0, s[46:47]
	s_mov_b32 m0, s19
	ds_read_b128 v[226:229], v0
	ds_read_b128 v[230:233], v0 offset:1024
	ds_read_b128 v[234:237], v0 offset:2048
	ds_read_b128 v[238:241], v0 offset:3072
	global_load_lds_dwordx4 v[242:243], off
	v_lshl_add_u64 v[242:243], v[244:245], 0, s[46:47]
	s_add_i32 m0, s19, 0x2000
	s_nop 0
	global_load_lds_dwordx4 v[242:243], off
	s_barrier
	s_waitcnt lgkmcnt(0)
	s_setprio 1
	s_waitcnt lgkmcnt(0)
	v_mfma_f32_16x16x32_bf16 v[118:121], v[226:229], v[182:185], v[118:121]
	v_mfma_f32_16x16x32_bf16 v[114:117], v[234:237], v[182:185], v[114:117]
	v_mfma_f32_16x16x32_bf16 v[102:105], v[226:229], v[190:193], v[102:105]
	v_mfma_f32_16x16x32_bf16 v[98:101], v[234:237], v[190:193], v[98:101]
	v_mfma_f32_16x16x32_bf16 v[86:89], v[226:229], v[210:213], v[86:89]
	v_mfma_f32_16x16x32_bf16 v[82:85], v[234:237], v[210:213], v[82:85]
	v_mfma_f32_16x16x32_bf16 v[70:73], v[226:229], v[218:221], v[70:73]
	v_mfma_f32_16x16x32_bf16 v[66:69], v[234:237], v[218:221], v[66:69]
	v_mfma_f32_16x16x32_bf16 v[118:121], v[230:233], v[186:189], v[118:121]
	v_mfma_f32_16x16x32_bf16 v[114:117], v[238:241], v[186:189], v[114:117]
	v_mfma_f32_16x16x32_bf16 v[102:105], v[230:233], v[206:209], v[102:105]
	v_mfma_f32_16x16x32_bf16 v[98:101], v[238:241], v[206:209], v[98:101]
	v_mfma_f32_16x16x32_bf16 v[86:89], v[230:233], v[214:217], v[86:89]
	v_mfma_f32_16x16x32_bf16 v[82:85], v[238:241], v[214:217], v[82:85]
	v_mfma_f32_16x16x32_bf16 v[70:73], v[230:233], v[222:225], v[70:73]
	v_mfma_f32_16x16x32_bf16 v[66:69], v[238:241], v[222:225], v[66:69]
	s_setprio 0
	s_mov_b32 m0, s14
	v_lshl_add_u64 v[242:243], v[246:247], 0, s[46:47]
	s_barrier
	ds_read_b128 v[182:185], v172 offset:49152
	ds_read_b128 v[186:189], v172 offset:50176
	ds_read_b128 v[190:193], v172 offset:51200
	ds_read_b128 v[206:209], v172 offset:52224
	ds_read_b128 v[210:213], v172 offset:53248
	ds_read_b128 v[214:217], v172 offset:54272
	ds_read_b128 v[218:221], v172 offset:55296
	ds_read_b128 v[222:225], v172 offset:56320
	global_load_lds_dwordx4 v[242:243], off
	v_lshl_add_u64 v[242:243], v[248:249], 0, s[46:47]
	s_mov_b32 m0, s15
	s_nop 0
	global_load_lds_dwordx4 v[242:243], off
	s_barrier
	s_waitcnt lgkmcnt(0)
	s_setprio 1
	s_waitcnt lgkmcnt(0)
	v_mfma_f32_16x16x32_bf16 v[62:65], v[158:161], v[182:185], v[62:65]
	v_mfma_f32_16x16x32_bf16 v[58:61], v[174:177], v[182:185], v[58:61]
	v_mfma_f32_16x16x32_bf16 v[46:49], v[158:161], v[190:193], v[46:49]
	v_mfma_f32_16x16x32_bf16 v[42:45], v[174:177], v[190:193], v[42:45]
	v_mfma_f32_16x16x32_bf16 v[30:33], v[158:161], v[210:213], v[30:33]
	v_mfma_f32_16x16x32_bf16 v[26:29], v[174:177], v[210:213], v[26:29]
	v_mfma_f32_16x16x32_bf16 v[14:17], v[158:161], v[218:221], v[14:17]
	v_mfma_f32_16x16x32_bf16 v[10:13], v[174:177], v[218:221], v[10:13]
	v_mfma_f32_16x16x32_bf16 v[62:65], v[162:165], v[186:189], v[62:65]
	v_mfma_f32_16x16x32_bf16 v[58:61], v[178:181], v[186:189], v[58:61]
	v_mfma_f32_16x16x32_bf16 v[46:49], v[162:165], v[206:209], v[46:49]
	v_mfma_f32_16x16x32_bf16 v[42:45], v[178:181], v[206:209], v[42:45]
	v_mfma_f32_16x16x32_bf16 v[30:33], v[162:165], v[214:217], v[30:33]
	v_mfma_f32_16x16x32_bf16 v[26:29], v[178:181], v[214:217], v[26:29]
	v_mfma_f32_16x16x32_bf16 v[14:17], v[162:165], v[222:225], v[14:17]
	v_mfma_f32_16x16x32_bf16 v[10:13], v[178:181], v[222:225], v[10:13]
	s_setprio 0
	s_barrier
	s_add_u32 s6, s6, 0x40080
	s_addc_u32 s7, s7, 0
	s_add_i32 s18, s18, s10
	v_lshl_add_u64 v[158:159], s[6:7], 0, v[132:133]
	s_mov_b32 m0, s18
	s_nop 0
	global_load_lds_dwordx4 v[158:159], off
	v_lshl_add_u64 v[158:159], s[6:7], 0, v[136:137]
	s_add_i32 m0, s18, 0x2000
	s_nop 0
	global_load_lds_dwordx4 v[158:159], off
	s_waitcnt vmcnt(6)
	s_barrier
	s_setprio 1
	v_mfma_f32_16x16x32_bf16 v[54:57], v[226:229], v[182:185], v[54:57]
	v_mfma_f32_16x16x32_bf16 v[50:53], v[234:237], v[182:185], v[50:53]
	v_mfma_f32_16x16x32_bf16 v[38:41], v[226:229], v[190:193], v[38:41]
	v_mfma_f32_16x16x32_bf16 v[34:37], v[234:237], v[190:193], v[34:37]
	v_mfma_f32_16x16x32_bf16 v[22:25], v[226:229], v[210:213], v[22:25]
	v_mfma_f32_16x16x32_bf16 v[18:21], v[234:237], v[210:213], v[18:21]
	v_mfma_f32_16x16x32_bf16 v[6:9], v[226:229], v[218:221], v[6:9]
	v_mfma_f32_16x16x32_bf16 v[2:5], v[234:237], v[218:221], v[2:5]
	v_mfma_f32_16x16x32_bf16 v[54:57], v[230:233], v[186:189], v[54:57]
	v_mfma_f32_16x16x32_bf16 v[50:53], v[238:241], v[186:189], v[50:53]
	v_mfma_f32_16x16x32_bf16 v[38:41], v[230:233], v[206:209], v[38:41]
	v_mfma_f32_16x16x32_bf16 v[34:37], v[238:241], v[206:209], v[34:37]
	v_mfma_f32_16x16x32_bf16 v[22:25], v[230:233], v[214:217], v[22:25]
	v_mfma_f32_16x16x32_bf16 v[18:21], v[238:241], v[214:217], v[18:21]
	v_mfma_f32_16x16x32_bf16 v[6:9], v[230:233], v[222:225], v[6:9]
	v_mfma_f32_16x16x32_bf16 v[2:5], v[238:241], v[222:225], v[2:5]
	s_setprio 0
	s_add_i32 s20, s20, 2
	s_add_u32 s40, s40, 0x100
	s_addc_u32 s41, s41, 0
	s_add_u32 s5, s5, 0x100
	s_addc_u32 s17, s17, 0
	s_cmp_gt_u32 s20, 13
	s_barrier
	s_cbranch_scc1 .Lmy_kexit0

.Lmy_kexit0:
	s_and_b32 s1, s0, -2
	s_cmp_eq_u32 s1, 4
	s_cselect_b64 s[42:43], -1, 0
	s_lshl_b32 s20, s16, 8
	s_add_i32 s20, s20, s70
	s_cmp_eq_u32 s0, 4
	s_mov_b32 s2, 0x4840000
	s_cselect_b32 s3, s2, 0x48c0000
	s_mov_b32 s2, 0x49c0000
	s_cselect_b32 s2, s2, 0x49d0000
	s_ashr_i32 s4, s20, 11
	s_ashr_i32 s5, s4, 31
	s_lshl_b64 s[18:19], s[4:5], 17
	v_or_b32_e32 v173, s20, v139
	s_cmp_lg_u32 s1, 4
	v_mov_b64_e32 v[160:161], 0
	v_cmp_gt_i32_e32 vcc, s94, v173
	s_cbranch_scc1 .LBB0_253
	s_and_saveexec_b64 s[4:5], vcc
	s_xor_b64 s[6:7], exec, s[4:5]
	s_cbranch_execz .LBB0_250
	s_lshl_b32 s1, s3, 2
	s_add_u32 s1, s84, s1
	v_and_b32_e32 v160, 0x7cf, v173
	s_addc_u32 s5, s85, 0
	v_add_u32_e32 v0, 0xfffff880, v160
	s_add_u32 s4, s1, s18
	v_lshlrev_b64 v[158:159], 10, v[0:1]
	s_addc_u32 s5, s5, s19
	s_movk_i32 s1, 0x77f
	v_lshl_add_u64 v[158:159], s[4:5], 0, v[158:159]
	v_cmp_lt_u32_e32 vcc, s1, v160
	s_nop 1
	v_cndmask_b32_e32 v161, 0, v159, vcc
	v_cndmask_b32_e32 v160, 0, v158, vcc

.LBB0_491:
	s_ashr_i32 s43, s42, 31
	s_xor_b64 s[92:93], s[18:19], -1
	s_lshl_b64 s[14:15], s[42:43], 19
	s_add_u32 s16, s86, s14
	s_addc_u32 s17, s87, s15
	s_and_b64 s[14:15], s[18:19], exec
	s_cselect_b32 s26, s17, s77
	s_cselect_b32 s27, s16, s76
	s_ashr_i32 s5, s4, 31
	s_lshl_b64 s[14:15], s[4:5], 19
	s_add_u32 s14, s8, s14
	s_addc_u32 s15, s9, s15
	s_and_b64 s[18:19], s[18:19], exec
	s_cselect_b32 s5, s15, s1
	s_cselect_b32 s18, s14, s0
	s_add_u32 vcc_lo, s76, 0x40080
	s_addc_u32 vcc_hi, s77, 0
	s_add_u32 s19, s0, 0x100
	s_waitcnt lgkmcnt(0)
	s_addc_u32 s43, s1, 0
	s_mov_b32 s61, -2
	s_add_u32 s0, vcc_lo, 0xfffc0080
	s_addc_u32 s1, vcc_hi, -1
	s_add_i32 s28, s69, 0x100
	v_add_u32_e32 v0, s28, v151
	ds_read_b128 v[158:161], v0
	ds_read_b128 v[162:165], v0 offset:1024
	ds_read_b128 v[166:169], v0 offset:2048
	ds_read_b128 v[170:173], v0 offset:3072
	s_cmp_eq_u32 s61, 12
	s_cselect_b32 s77, s26, s1
	s_cselect_b32 s76, s27, s0
	s_cselect_b32 s1, s5, s43
	s_cselect_b32 s0, s18, s19
	v_lshl_add_u64 v[154:155], vcc, 0, v[140:141]
	s_add_i32 m0, s11, 0xc000
	ds_read_b128 v[174:177], v156
	ds_read_b128 v[178:181], v156 offset:1024
	ds_read_b128 v[182:185], v156 offset:2048
	ds_read_b128 v[186:189], v156 offset:3072
	ds_read_b128 v[190:193], v156 offset:4096
	ds_read_b128 v[206:209], v156 offset:5120
	ds_read_b128 v[210:213], v156 offset:6144
	ds_read_b128 v[214:217], v156 offset:7168
	global_load_lds_dwordx4 v[154:155], off
	v_lshl_add_u64 v[154:155], vcc, 0, v[142:143]
	s_add_i32 m0, s11, 0xe000
	s_nop 0
	global_load_lds_dwordx4 v[154:155], off
	s_waitcnt lgkmcnt(8)
	s_barrier
	s_waitcnt lgkmcnt(0)
	s_setprio 1
	s_waitcnt lgkmcnt(0)
	v_mfma_f32_16x16x32_bf16 v[126:129], v[158:161], v[174:177], 0
	v_mfma_f32_16x16x32_bf16 v[122:125], v[166:169], v[174:177], 0
	v_mfma_f32_16x16x32_bf16 v[110:113], v[158:161], v[182:185], 0
	v_mfma_f32_16x16x32_bf16 v[106:109], v[166:169], v[182:185], 0
	v_mfma_f32_16x16x32_bf16 v[94:97], v[158:161], v[190:193], 0
	v_mfma_f32_16x16x32_bf16 v[90:93], v[166:169], v[190:193], 0
	v_mfma_f32_16x16x32_bf16 v[78:81], v[158:161], v[210:213], 0
	v_mfma_f32_16x16x32_bf16 v[74:77], v[166:169], v[210:213], 0
	v_mfma_f32_16x16x32_bf16 v[126:129], v[162:165], v[178:181], v[126:129]
	v_mfma_f32_16x16x32_bf16 v[122:125], v[170:173], v[178:181], v[122:125]
	v_mfma_f32_16x16x32_bf16 v[110:113], v[162:165], v[186:189], v[110:113]
	v_mfma_f32_16x16x32_bf16 v[106:109], v[170:173], v[186:189], v[106:109]
	v_mfma_f32_16x16x32_bf16 v[94:97], v[162:165], v[206:209], v[94:97]
	v_mfma_f32_16x16x32_bf16 v[90:93], v[170:173], v[206:209], v[90:93]
	v_mfma_f32_16x16x32_bf16 v[78:81], v[162:165], v[214:217], v[78:81]
	v_mfma_f32_16x16x32_bf16 v[74:77], v[170:173], v[214:217], v[74:77]
	s_setprio 0
	s_barrier
	s_add_i32 s63, s96, 0x100
	s_add_i32 s28, s28, s3
	v_add_u32_e32 v0, s63, v151
	v_lshl_add_u64 v[154:155], s[0:1], 0, v[132:133]
	s_mov_b32 m0, s28
	ds_read_b128 v[218:221], v0
	ds_read_b128 v[222:225], v0 offset:1024
	ds_read_b128 v[226:229], v0 offset:2048
	ds_read_b128 v[230:233], v0 offset:3072
	global_load_lds_dwordx4 v[154:155], off
	v_lshl_add_u64 v[234:235], s[0:1], 0, v[136:137]
	s_add_i32 m0, s28, 0x2000
	s_nop 0
	global_load_lds_dwordx4 v[234:235], off
	s_barrier
	s_waitcnt lgkmcnt(0)
	s_setprio 1
	s_waitcnt lgkmcnt(0)
	v_mfma_f32_16x16x32_bf16 v[118:121], v[218:221], v[174:177], 0
	v_mfma_f32_16x16x32_bf16 v[114:117], v[226:229], v[174:177], 0
	v_mfma_f32_16x16x32_bf16 v[102:105], v[218:221], v[182:185], 0
	v_mfma_f32_16x16x32_bf16 v[98:101], v[226:229], v[182:185], 0
	v_mfma_f32_16x16x32_bf16 v[86:89], v[218:221], v[190:193], 0
	v_mfma_f32_16x16x32_bf16 v[82:85], v[226:229], v[190:193], 0
	v_mfma_f32_16x16x32_bf16 v[70:73], v[218:221], v[210:213], 0
	v_mfma_f32_16x16x32_bf16 v[66:69], v[226:229], v[210:213], 0
	v_mfma_f32_16x16x32_bf16 v[118:121], v[222:225], v[178:181], v[118:121]
	v_mfma_f32_16x16x32_bf16 v[114:117], v[230:233], v[178:181], v[114:117]
	v_mfma_f32_16x16x32_bf16 v[102:105], v[222:225], v[186:189], v[102:105]
	v_mfma_f32_16x16x32_bf16 v[98:101], v[230:233], v[186:189], v[98:101]
	v_mfma_f32_16x16x32_bf16 v[86:89], v[222:225], v[206:209], v[86:89]
	v_mfma_f32_16x16x32_bf16 v[82:85], v[230:233], v[206:209], v[82:85]
	v_mfma_f32_16x16x32_bf16 v[70:73], v[222:225], v[214:217], v[70:73]
	v_mfma_f32_16x16x32_bf16 v[66:69], v[230:233], v[214:217], v[66:69]
	s_setprio 0
	s_mov_b32 m0, s11
	v_lshl_add_u64 v[236:237], s[76:77], 0, v[130:131]
	s_barrier
	ds_read_b128 v[174:177], v156 offset:16384
	ds_read_b128 v[178:181], v156 offset:17408
	ds_read_b128 v[182:185], v156 offset:18432
	ds_read_b128 v[186:189], v156 offset:19456
	ds_read_b128 v[190:193], v156 offset:20480
	ds_read_b128 v[206:209], v156 offset:21504
	ds_read_b128 v[210:213], v156 offset:22528
	ds_read_b128 v[214:217], v156 offset:23552
	global_load_lds_dwordx4 v[236:237], off
	v_lshl_add_u64 v[238:239], s[76:77], 0, v[134:135]
	s_mov_b32 m0, s12
	s_nop 0
	global_load_lds_dwordx4 v[238:239], off
	s_barrier
	s_waitcnt lgkmcnt(0)
	s_setprio 1
	s_waitcnt lgkmcnt(0)
	v_mfma_f32_16x16x32_bf16 v[62:65], v[158:161], v[174:177], 0
	v_mfma_f32_16x16x32_bf16 v[58:61], v[166:169], v[174:177], 0
	v_mfma_f32_16x16x32_bf16 v[46:49], v[158:161], v[182:185], 0
	v_mfma_f32_16x16x32_bf16 v[42:45], v[166:169], v[182:185], 0
	v_mfma_f32_16x16x32_bf16 v[30:33], v[158:161], v[190:193], 0
	v_mfma_f32_16x16x32_bf16 v[26:29], v[166:169], v[190:193], 0
	v_mfma_f32_16x16x32_bf16 v[14:17], v[158:161], v[210:213], 0
	v_mfma_f32_16x16x32_bf16 v[10:13], v[166:169], v[210:213], 0
	v_mfma_f32_16x16x32_bf16 v[62:65], v[162:165], v[178:181], v[62:65]
	v_mfma_f32_16x16x32_bf16 v[58:61], v[170:173], v[178:181], v[58:61]
	v_mfma_f32_16x16x32_bf16 v[46:49], v[162:165], v[186:189], v[46:49]
	v_mfma_f32_16x16x32_bf16 v[42:45], v[170:173], v[186:189], v[42:45]
	v_mfma_f32_16x16x32_bf16 v[30:33], v[162:165], v[206:209], v[30:33]
	v_mfma_f32_16x16x32_bf16 v[26:29], v[170:173], v[206:209], v[26:29]
	v_mfma_f32_16x16x32_bf16 v[14:17], v[162:165], v[214:217], v[14:17]
	v_mfma_f32_16x16x32_bf16 v[10:13], v[170:173], v[214:217], v[10:13]
	s_setprio 0
	s_barrier
	s_add_u32 s28, s0, 0x40000
	s_addc_u32 s29, s1, 0
	s_add_i32 s63, s63, s3
	v_lshl_add_u64 v[158:159], s[28:29], 0, v[132:133]
	s_mov_b32 m0, s63
	s_nop 0
	global_load_lds_dwordx4 v[158:159], off
	v_lshl_add_u64 v[158:159], s[28:29], 0, v[136:137]
	s_add_i32 m0, s63, 0x2000
	s_nop 0
	global_load_lds_dwordx4 v[158:159], off
	s_waitcnt vmcnt(6)
	s_barrier
	s_setprio 1
	v_mfma_f32_16x16x32_bf16 v[54:57], v[218:221], v[174:177], 0
	v_mfma_f32_16x16x32_bf16 v[50:53], v[226:229], v[174:177], 0
	v_mfma_f32_16x16x32_bf16 v[38:41], v[218:221], v[182:185], 0
	v_mfma_f32_16x16x32_bf16 v[34:37], v[226:229], v[182:185], 0
	v_mfma_f32_16x16x32_bf16 v[22:25], v[218:221], v[190:193], 0
	v_mfma_f32_16x16x32_bf16 v[18:21], v[226:229], v[190:193], 0
	v_mfma_f32_16x16x32_bf16 v[6:9], v[218:221], v[210:213], 0
	v_mfma_f32_16x16x32_bf16 v[2:5], v[226:229], v[210:213], 0
	v_mfma_f32_16x16x32_bf16 v[54:57], v[222:225], v[178:181], v[54:57]
	v_mfma_f32_16x16x32_bf16 v[50:53], v[230:233], v[178:181], v[50:53]
	v_mfma_f32_16x16x32_bf16 v[38:41], v[222:225], v[186:189], v[38:41]
	v_mfma_f32_16x16x32_bf16 v[34:37], v[230:233], v[186:189], v[34:37]
	v_mfma_f32_16x16x32_bf16 v[22:25], v[222:225], v[206:209], v[22:25]
	v_mfma_f32_16x16x32_bf16 v[18:21], v[230:233], v[206:209], v[18:21]
	v_mfma_f32_16x16x32_bf16 v[6:9], v[222:225], v[214:217], v[6:9]
	v_mfma_f32_16x16x32_bf16 v[2:5], v[230:233], v[214:217], v[2:5]
	s_setprio 0
	s_add_i32 s63, s97, 0x100
	v_add_u32_e32 v0, s63, v151
	s_barrier
	ds_read_b128 v[158:161], v0
	ds_read_b128 v[162:165], v0 offset:1024
	ds_read_b128 v[166:169], v0 offset:2048
	ds_read_b128 v[170:173], v0 offset:3072
	s_add_u32 s28, s76, 0x40000
	s_addc_u32 s29, s77, 0
	s_mov_b32 m0, s13
	v_lshl_add_u64 v[218:219], s[28:29], 0, v[130:131]
	ds_read_b128 v[174:177], v156 offset:32768
	ds_read_b128 v[178:181], v156 offset:33792
	ds_read_b128 v[182:185], v156 offset:34816
	ds_read_b128 v[186:189], v156 offset:35840
	ds_read_b128 v[190:193], v156 offset:36864
	ds_read_b128 v[206:209], v156 offset:37888
	ds_read_b128 v[210:213], v156 offset:38912
	ds_read_b128 v[214:217], v156 offset:39936
	global_load_lds_dwordx4 v[218:219], off
	v_lshl_add_u64 v[218:219], s[28:29], 0, v[134:135]
	s_mov_b32 m0, s20
	s_nop 0
	global_load_lds_dwordx4 v[218:219], off
	s_waitcnt lgkmcnt(8)
	s_barrier
	s_waitcnt lgkmcnt(0)
	s_setprio 1
	s_waitcnt lgkmcnt(0)
	v_mfma_f32_16x16x32_bf16 v[126:129], v[158:161], v[174:177], v[126:129]
	v_mfma_f32_16x16x32_bf16 v[122:125], v[166:169], v[174:177], v[122:125]
	v_mfma_f32_16x16x32_bf16 v[110:113], v[158:161], v[182:185], v[110:113]
	v_mfma_f32_16x16x32_bf16 v[106:109], v[166:169], v[182:185], v[106:109]
	v_mfma_f32_16x16x32_bf16 v[94:97], v[158:161], v[190:193], v[94:97]
	v_mfma_f32_16x16x32_bf16 v[90:93], v[166:169], v[190:193], v[90:93]
	v_mfma_f32_16x16x32_bf16 v[78:81], v[158:161], v[210:213], v[78:81]
	v_mfma_f32_16x16x32_bf16 v[74:77], v[166:169], v[210:213], v[74:77]
	v_mfma_f32_16x16x32_bf16 v[126:129], v[162:165], v[178:181], v[126:129]
	v_mfma_f32_16x16x32_bf16 v[122:125], v[170:173], v[178:181], v[122:125]
	v_mfma_f32_16x16x32_bf16 v[110:113], v[162:165], v[186:189], v[110:113]
	v_mfma_f32_16x16x32_bf16 v[106:109], v[170:173], v[186:189], v[106:109]
	v_mfma_f32_16x16x32_bf16 v[94:97], v[162:165], v[206:209], v[94:97]
	v_mfma_f32_16x16x32_bf16 v[90:93], v[170:173], v[206:209], v[90:93]
	v_mfma_f32_16x16x32_bf16 v[78:81], v[162:165], v[214:217], v[78:81]
	v_mfma_f32_16x16x32_bf16 v[74:77], v[170:173], v[214:217], v[74:77]
	s_setprio 0
	s_barrier
	s_add_i32 s28, s44, 0x100
	s_add_i32 s29, s63, s3
	v_add_u32_e32 v0, s28, v151
	v_lshl_add_u64 v[154:155], v[154:155], 0, s[46:47]
	s_mov_b32 m0, s29
	ds_read_b128 v[218:221], v0
	ds_read_b128 v[222:225], v0 offset:1024
	ds_read_b128 v[226:229], v0 offset:2048
	ds_read_b128 v[230:233], v0 offset:3072
	global_load_lds_dwordx4 v[154:155], off
	v_lshl_add_u64 v[154:155], v[234:235], 0, s[46:47]
	s_add_i32 m0, s29, 0x2000
	s_nop 0
	global_load_lds_dwordx4 v[154:155], off
	s_barrier
	s_waitcnt lgkmcnt(0)
	s_setprio 1
	s_waitcnt lgkmcnt(0)
	v_mfma_f32_16x16x32_bf16 v[118:121], v[218:221], v[174:177], v[118:121]
	v_mfma_f32_16x16x32_bf16 v[114:117], v[226:229], v[174:177], v[114:117]
	v_mfma_f32_16x16x32_bf16 v[102:105], v[218:221], v[182:185], v[102:105]
	v_mfma_f32_16x16x32_bf16 v[98:101], v[226:229], v[182:185], v[98:101]
	v_mfma_f32_16x16x32_bf16 v[86:89], v[218:221], v[190:193], v[86:89]
	v_mfma_f32_16x16x32_bf16 v[82:85], v[226:229], v[190:193], v[82:85]
	v_mfma_f32_16x16x32_bf16 v[70:73], v[218:221], v[210:213], v[70:73]
	v_mfma_f32_16x16x32_bf16 v[66:69], v[226:229], v[210:213], v[66:69]
	v_mfma_f32_16x16x32_bf16 v[118:121], v[222:225], v[178:181], v[118:121]
	v_mfma_f32_16x16x32_bf16 v[114:117], v[230:233], v[178:181], v[114:117]
	v_mfma_f32_16x16x32_bf16 v[102:105], v[222:225], v[186:189], v[102:105]
	v_mfma_f32_16x16x32_bf16 v[98:101], v[230:233], v[186:189], v[98:101]
	v_mfma_f32_16x16x32_bf16 v[86:89], v[222:225], v[206:209], v[86:89]
	v_mfma_f32_16x16x32_bf16 v[82:85], v[230:233], v[206:209], v[82:85]
	v_mfma_f32_16x16x32_bf16 v[70:73], v[222:225], v[214:217], v[70:73]
	v_mfma_f32_16x16x32_bf16 v[66:69], v[230:233], v[214:217], v[66:69]
	s_setprio 0
	s_mov_b32 m0, s23
	v_lshl_add_u64 v[154:155], v[236:237], 0, s[46:47]
	s_barrier
	ds_read_b128 v[174:177], v156 offset:49152
	ds_read_b128 v[178:181], v156 offset:50176
	ds_read_b128 v[182:185], v156 offset:51200
	ds_read_b128 v[186:189], v156 offset:52224
	ds_read_b128 v[190:193], v156 offset:53248
	ds_read_b128 v[206:209], v156 offset:54272
	ds_read_b128 v[210:213], v156 offset:55296
	ds_read_b128 v[214:217], v156 offset:56320
	global_load_lds_dwordx4 v[154:155], off
	v_lshl_add_u64 v[154:155], v[238:239], 0, s[46:47]
	s_mov_b32 m0, s24
	s_nop 0
	global_load_lds_dwordx4 v[154:155], off
	s_barrier
	s_waitcnt lgkmcnt(0)
	s_setprio 1
	s_waitcnt lgkmcnt(0)
	v_mfma_f32_16x16x32_bf16 v[62:65], v[158:161], v[174:177], v[62:65]
	v_mfma_f32_16x16x32_bf16 v[58:61], v[166:169], v[174:177], v[58:61]
	v_mfma_f32_16x16x32_bf16 v[46:49], v[158:161], v[182:185], v[46:49]
	v_mfma_f32_16x16x32_bf16 v[42:45], v[166:169], v[182:185], v[42:45]
	v_mfma_f32_16x16x32_bf16 v[30:33], v[158:161], v[190:193], v[30:33]
	v_mfma_f32_16x16x32_bf16 v[26:29], v[166:169], v[190:193], v[26:29]
	v_mfma_f32_16x16x32_bf16 v[14:17], v[158:161], v[210:213], v[14:17]
	v_mfma_f32_16x16x32_bf16 v[10:13], v[166:169], v[210:213], v[10:13]
	v_mfma_f32_16x16x32_bf16 v[62:65], v[162:165], v[178:181], v[62:65]
	v_mfma_f32_16x16x32_bf16 v[58:61], v[170:173], v[178:181], v[58:61]
	v_mfma_f32_16x16x32_bf16 v[46:49], v[162:165], v[186:189], v[46:49]
	v_mfma_f32_16x16x32_bf16 v[42:45], v[170:173], v[186:189], v[42:45]
	v_mfma_f32_16x16x32_bf16 v[30:33], v[162:165], v[206:209], v[30:33]
	v_mfma_f32_16x16x32_bf16 v[26:29], v[170:173], v[206:209], v[26:29]
	v_mfma_f32_16x16x32_bf16 v[14:17], v[162:165], v[214:217], v[14:17]
	v_mfma_f32_16x16x32_bf16 v[10:13], v[170:173], v[214:217], v[10:13]
	s_setprio 0
	s_barrier
	s_add_u32 s0, s0, 0x40080
	s_addc_u32 s1, s1, 0
	s_add_i32 s28, s28, s3
	v_lshl_add_u64 v[154:155], s[0:1], 0, v[132:133]
	s_mov_b32 m0, s28
	s_nop 0
	global_load_lds_dwordx4 v[154:155], off
	v_lshl_add_u64 v[154:155], s[0:1], 0, v[136:137]
	s_add_i32 m0, s28, 0x2000
	s_nop 0
	global_load_lds_dwordx4 v[154:155], off
	s_waitcnt vmcnt(6)
	s_barrier
	s_setprio 1
	v_mfma_f32_16x16x32_bf16 v[54:57], v[218:221], v[174:177], v[54:57]
	v_mfma_f32_16x16x32_bf16 v[50:53], v[226:229], v[174:177], v[50:53]
	v_mfma_f32_16x16x32_bf16 v[38:41], v[218:221], v[182:185], v[38:41]
	v_mfma_f32_16x16x32_bf16 v[34:37], v[226:229], v[182:185], v[34:37]
	v_mfma_f32_16x16x32_bf16 v[22:25], v[218:221], v[190:193], v[22:25]
	v_mfma_f32_16x16x32_bf16 v[18:21], v[226:229], v[190:193], v[18:21]
	v_mfma_f32_16x16x32_bf16 v[6:9], v[218:221], v[210:213], v[6:9]
	v_mfma_f32_16x16x32_bf16 v[2:5], v[226:229], v[210:213], v[2:5]
	v_mfma_f32_16x16x32_bf16 v[54:57], v[222:225], v[178:181], v[54:57]
	v_mfma_f32_16x16x32_bf16 v[50:53], v[230:233], v[178:181], v[50:53]
	v_mfma_f32_16x16x32_bf16 v[38:41], v[222:225], v[186:189], v[38:41]
	v_mfma_f32_16x16x32_bf16 v[34:37], v[230:233], v[186:189], v[34:37]
	v_mfma_f32_16x16x32_bf16 v[22:25], v[222:225], v[206:209], v[22:25]
	v_mfma_f32_16x16x32_bf16 v[18:21], v[230:233], v[206:209], v[18:21]
	v_mfma_f32_16x16x32_bf16 v[6:9], v[222:225], v[214:217], v[6:9]
	v_mfma_f32_16x16x32_bf16 v[2:5], v[230:233], v[214:217], v[2:5]
	s_setprio 0
	s_add_i32 s61, s61, 2
	s_add_u32 vcc_lo, vcc_lo, 0x100
	s_addc_u32 vcc_hi, vcc_hi, 0
	s_add_u32 s19, s19, 0x100
	s_addc_u32 s43, s43, 0
	s_cmp_gt_u32 s61, 13
	s_barrier
	s_cbranch_scc1 .Lmy_kexit1

.Lmy_kexit1:
	v_lshl_add_u32 v154, s62, 8, v139
	v_ashrrev_i32_e32 v155, 31, v154
	s_lshl_b32 s62, s60, 8
	v_lshlrev_b64 v[158:159], 11, v[154:155]
	s_ashr_i32 s63, s62, 31
	v_lshl_add_u64 v[158:159], s[78:79], 0, v[158:159]
	v_lshl_add_u64 v[158:159], s[62:63], 1, v[158:159]
	s_lshl_b32 s70, s22, 1
	v_lshl_add_u64 v[158:159], v[158:159], 0, s[70:71]
	v_lshlrev_b32_e32 v0, 1, v138
	v_lshl_add_u64 v[162:163], v[158:159], 0, v[0:1]
	v_cvt_pk_bf16_f32 v158, v126, v127
	v_mul_f32_e32 v127, v127, v127
	v_fmac_f32_e32 v127, v126, v126
	v_mul_f32_e32 v126, v119, v119
	v_fmac_f32_e32 v126, v118, v118
	v_fmac_f32_e32 v127, v128, v128
	v_fmac_f32_e32 v126, v120, v120
	v_fmac_f32_e32 v127, v129, v129
	v_fmac_f32_e32 v126, v121, v121
	v_fmac_f32_e32 v127, v122, v122
	v_fmac_f32_e32 v126, v114, v114
	v_fmac_f32_e32 v127, v123, v123
	v_fmac_f32_e32 v126, v115, v115
	v_fmac_f32_e32 v127, v124, v124
	v_fmac_f32_e32 v126, v116, v116
	v_cvt_pk_bf16_f32 v159, v128, v129
	v_fmac_f32_e32 v127, v125, v125
	v_fmac_f32_e32 v126, v117, v117
	v_and_b32_e32 v128, 64, v199
	v_add_f32_e32 v127, v127, v126
	v_xor_b32_e32 v126, 16, v199
	v_add_u32_e32 v128, 64, v128
	v_cmp_lt_i32_e32 vcc, v126, v128
	v_cvt_pk_bf16_f32 v160, v122, v123
	v_cvt_pk_bf16_f32 v161, v124, v125
	global_store_dwordx4 v[162:163], v[158:161], off
	s_lshl_b32 s60, s60, 2
	v_cndmask_b32_e32 v126, v199, v126, vcc
	v_lshlrev_b32_e32 v126, 2, v126
	ds_bpermute_b32 v129, v126, v127
	v_cvt_pk_bf16_f32 v158, v118, v119
	v_xor_b32_e32 v118, 32, v199
	v_cmp_lt_i32_e32 vcc, v118, v128
	s_ashr_i32 s61, s60, 31
	s_waitcnt lgkmcnt(0)
	v_add_f32_e32 v119, v127, v129
	v_cndmask_b32_e32 v118, v199, v118, vcc
	v_lshlrev_b32_e32 v118, 2, v118
	ds_bpermute_b32 v122, v118, v119
	v_cvt_pk_bf16_f32 v159, v120, v121
	v_cvt_pk_bf16_f32 v160, v114, v115
	v_cvt_pk_bf16_f32 v161, v116, v117
	global_store_dwordx4 v[162:163], v[158:161], off offset:256
	s_and_saveexec_b64 s[0:1], s[40:41]
	s_cbranch_execz .LBB0_495
	v_lshlrev_b64 v[114:115], 6, v[154:155]
	v_lshl_add_u64 v[114:115], s[66:67], 0, v[114:115]
	v_lshl_add_u64 v[114:115], s[60:61], 2, v[114:115]
	s_lshl_b32 s18, s21, 2
	s_mov_b32 s19, s71
	s_waitcnt lgkmcnt(0)
	v_add_f32_e32 v116, v119, v122
	v_lshl_add_u64 v[114:115], v[114:115], 0, s[18:19]
	global_store_dword v[114:115], v116, off

.LBB0_888:
	s_ashr_i32 s5, s4, 31
	s_xor_b64 s[76:77], s[42:43], -1
	s_lshl_b64 s[24:25], s[4:5], 19
	s_add_u32 s40, s86, s24
	s_addc_u32 s41, s87, s25
	s_and_b64 s[24:25], s[42:43], exec
	s_cselect_b32 s5, s41, s63
	s_cselect_b32 s24, s40, s62
	s_ashr_i32 s7, s6, 31
	s_lshl_b64 s[26:27], s[6:7], 19
	s_add_u32 s92, s72, s26
	s_addc_u32 s93, s73, s27
	s_and_b64 s[26:27], s[42:43], exec
	s_cselect_b32 s7, s93, s1
	s_cselect_b32 s25, s92, s0
	s_add_u32 vcc_lo, s62, 0x40080
	s_addc_u32 vcc_hi, s63, 0
	s_add_u32 s26, s0, 0x100
	s_addc_u32 s27, s1, 0
	s_mov_b32 s42, -2
	s_add_u32 s0, vcc_lo, 0xfffc0080
	s_addc_u32 s1, vcc_hi, -1
	s_add_i32 s28, s69, 0x100
	v_add_u32_e32 v0, s28, v151
	ds_read_b128 v[154:157], v0
	ds_read_b128 v[170:173], v0 offset:1024
	ds_read_b128 v[174:177], v0 offset:2048
	ds_read_b128 v[178:181], v0 offset:3072
	s_cmp_eq_u32 s42, 12
	s_cselect_b32 s63, s5, s1
	s_cselect_b32 s62, s24, s0
	s_cselect_b32 s1, s7, s27
	s_cselect_b32 s0, s25, s26
	v_lshl_add_u64 v[158:159], vcc, 0, v[140:141]
	s_add_i32 m0, s9, 0xc000
	ds_read_b128 v[182:185], v168
	ds_read_b128 v[186:189], v168 offset:1024
	ds_read_b128 v[190:193], v168 offset:2048
	ds_read_b128 v[206:209], v168 offset:3072
	ds_read_b128 v[210:213], v168 offset:4096
	ds_read_b128 v[214:217], v168 offset:5120
	ds_read_b128 v[218:221], v168 offset:6144
	ds_read_b128 v[222:225], v168 offset:7168
	global_load_lds_dwordx4 v[158:159], off
	v_lshl_add_u64 v[158:159], vcc, 0, v[142:143]
	s_add_i32 m0, s9, 0xe000
	s_nop 0
	global_load_lds_dwordx4 v[158:159], off
	s_waitcnt lgkmcnt(8)
	s_barrier
	s_waitcnt lgkmcnt(0)
	s_setprio 1
	s_waitcnt lgkmcnt(0)
	v_mfma_f32_16x16x32_bf16 v[126:129], v[154:157], v[182:185], 0
	v_mfma_f32_16x16x32_bf16 v[122:125], v[174:177], v[182:185], 0
	v_mfma_f32_16x16x32_bf16 v[110:113], v[154:157], v[190:193], 0
	v_mfma_f32_16x16x32_bf16 v[106:109], v[174:177], v[190:193], 0
	v_mfma_f32_16x16x32_bf16 v[94:97], v[154:157], v[210:213], 0
	v_mfma_f32_16x16x32_bf16 v[90:93], v[174:177], v[210:213], 0
	v_mfma_f32_16x16x32_bf16 v[78:81], v[154:157], v[218:221], 0
	v_mfma_f32_16x16x32_bf16 v[74:77], v[174:177], v[218:221], 0
	v_mfma_f32_16x16x32_bf16 v[126:129], v[170:173], v[186:189], v[126:129]
	v_mfma_f32_16x16x32_bf16 v[122:125], v[178:181], v[186:189], v[122:125]
	v_mfma_f32_16x16x32_bf16 v[110:113], v[170:173], v[206:209], v[110:113]
	v_mfma_f32_16x16x32_bf16 v[106:109], v[178:181], v[206:209], v[106:109]
	v_mfma_f32_16x16x32_bf16 v[94:97], v[170:173], v[214:217], v[94:97]
	v_mfma_f32_16x16x32_bf16 v[90:93], v[178:181], v[214:217], v[90:93]
	v_mfma_f32_16x16x32_bf16 v[78:81], v[170:173], v[222:225], v[78:81]
	v_mfma_f32_16x16x32_bf16 v[74:77], v[178:181], v[222:225], v[74:77]
	s_setprio 0
	s_barrier
	s_add_i32 s43, s96, 0x100
	s_add_i32 s28, s28, s8
	v_add_u32_e32 v0, s43, v151
	v_lshl_add_u64 v[158:159], s[0:1], 0, v[132:133]
	s_mov_b32 m0, s28
	ds_read_b128 v[226:229], v0
	ds_read_b128 v[230:233], v0 offset:1024
	ds_read_b128 v[234:237], v0 offset:2048
	ds_read_b128 v[238:241], v0 offset:3072
	global_load_lds_dwordx4 v[158:159], off
	v_lshl_add_u64 v[242:243], s[0:1], 0, v[136:137]
	s_add_i32 m0, s28, 0x2000
	s_nop 0
	global_load_lds_dwordx4 v[242:243], off
	s_barrier
	s_waitcnt lgkmcnt(0)
	s_setprio 1
	s_waitcnt lgkmcnt(0)
	v_mfma_f32_16x16x32_bf16 v[118:121], v[226:229], v[182:185], 0
	v_mfma_f32_16x16x32_bf16 v[114:117], v[234:237], v[182:185], 0
	v_mfma_f32_16x16x32_bf16 v[102:105], v[226:229], v[190:193], 0
	v_mfma_f32_16x16x32_bf16 v[98:101], v[234:237], v[190:193], 0
	v_mfma_f32_16x16x32_bf16 v[86:89], v[226:229], v[210:213], 0
	v_mfma_f32_16x16x32_bf16 v[82:85], v[234:237], v[210:213], 0
	v_mfma_f32_16x16x32_bf16 v[70:73], v[226:229], v[218:221], 0
	v_mfma_f32_16x16x32_bf16 v[66:69], v[234:237], v[218:221], 0
	v_mfma_f32_16x16x32_bf16 v[118:121], v[230:233], v[186:189], v[118:121]
	v_mfma_f32_16x16x32_bf16 v[114:117], v[238:241], v[186:189], v[114:117]
	v_mfma_f32_16x16x32_bf16 v[102:105], v[230:233], v[206:209], v[102:105]
	v_mfma_f32_16x16x32_bf16 v[98:101], v[238:241], v[206:209], v[98:101]
	v_mfma_f32_16x16x32_bf16 v[86:89], v[230:233], v[214:217], v[86:89]
	v_mfma_f32_16x16x32_bf16 v[82:85], v[238:241], v[214:217], v[82:85]
	v_mfma_f32_16x16x32_bf16 v[70:73], v[230:233], v[222:225], v[70:73]
	v_mfma_f32_16x16x32_bf16 v[66:69], v[238:241], v[222:225], v[66:69]
	s_setprio 0
	s_mov_b32 m0, s9
	v_lshl_add_u64 v[244:245], s[62:63], 0, v[130:131]
	s_barrier
	ds_read_b128 v[182:185], v168 offset:16384
	ds_read_b128 v[186:189], v168 offset:17408
	ds_read_b128 v[190:193], v168 offset:18432
	ds_read_b128 v[206:209], v168 offset:19456
	ds_read_b128 v[210:213], v168 offset:20480
	ds_read_b128 v[214:217], v168 offset:21504
	ds_read_b128 v[218:221], v168 offset:22528
	ds_read_b128 v[222:225], v168 offset:23552
	global_load_lds_dwordx4 v[244:245], off
	v_lshl_add_u64 v[246:247], s[62:63], 0, v[134:135]
	s_mov_b32 m0, s10
	s_nop 0
	global_load_lds_dwordx4 v[246:247], off
	s_barrier
	s_waitcnt lgkmcnt(0)
	s_setprio 1
	s_waitcnt lgkmcnt(0)
	v_mfma_f32_16x16x32_bf16 v[62:65], v[154:157], v[182:185], 0
	v_mfma_f32_16x16x32_bf16 v[58:61], v[174:177], v[182:185], 0
	v_mfma_f32_16x16x32_bf16 v[46:49], v[154:157], v[190:193], 0
	v_mfma_f32_16x16x32_bf16 v[42:45], v[174:177], v[190:193], 0
	v_mfma_f32_16x16x32_bf16 v[30:33], v[154:157], v[210:213], 0
	v_mfma_f32_16x16x32_bf16 v[26:29], v[174:177], v[210:213], 0
	v_mfma_f32_16x16x32_bf16 v[14:17], v[154:157], v[218:221], 0
	v_mfma_f32_16x16x32_bf16 v[10:13], v[174:177], v[218:221], 0
	v_mfma_f32_16x16x32_bf16 v[62:65], v[170:173], v[186:189], v[62:65]
	v_mfma_f32_16x16x32_bf16 v[58:61], v[178:181], v[186:189], v[58:61]
	v_mfma_f32_16x16x32_bf16 v[46:49], v[170:173], v[206:209], v[46:49]
	v_mfma_f32_16x16x32_bf16 v[42:45], v[178:181], v[206:209], v[42:45]
	v_mfma_f32_16x16x32_bf16 v[30:33], v[170:173], v[214:217], v[30:33]
	v_mfma_f32_16x16x32_bf16 v[26:29], v[178:181], v[214:217], v[26:29]
	v_mfma_f32_16x16x32_bf16 v[14:17], v[170:173], v[222:225], v[14:17]
	v_mfma_f32_16x16x32_bf16 v[10:13], v[178:181], v[222:225], v[10:13]
	s_setprio 0
	s_barrier
	s_add_u32 s28, s0, 0x40000
	s_addc_u32 s29, s1, 0
	s_add_i32 s43, s43, s8
	v_lshl_add_u64 v[154:155], s[28:29], 0, v[132:133]
	s_mov_b32 m0, s43
	s_nop 0
	global_load_lds_dwordx4 v[154:155], off
	v_lshl_add_u64 v[154:155], s[28:29], 0, v[136:137]
	s_add_i32 m0, s43, 0x2000
	s_nop 0
	global_load_lds_dwordx4 v[154:155], off
	s_waitcnt vmcnt(6)
	s_barrier
	s_setprio 1
	v_mfma_f32_16x16x32_bf16 v[54:57], v[226:229], v[182:185], 0
	v_mfma_f32_16x16x32_bf16 v[50:53], v[234:237], v[182:185], 0
	v_mfma_f32_16x16x32_bf16 v[38:41], v[226:229], v[190:193], 0
	v_mfma_f32_16x16x32_bf16 v[34:37], v[234:237], v[190:193], 0
	v_mfma_f32_16x16x32_bf16 v[22:25], v[226:229], v[210:213], 0
	v_mfma_f32_16x16x32_bf16 v[18:21], v[234:237], v[210:213], 0
	v_mfma_f32_16x16x32_bf16 v[6:9], v[226:229], v[218:221], 0
	v_mfma_f32_16x16x32_bf16 v[2:5], v[234:237], v[218:221], 0
	v_mfma_f32_16x16x32_bf16 v[54:57], v[230:233], v[186:189], v[54:57]
	v_mfma_f32_16x16x32_bf16 v[50:53], v[238:241], v[186:189], v[50:53]
	v_mfma_f32_16x16x32_bf16 v[38:41], v[230:233], v[206:209], v[38:41]
	v_mfma_f32_16x16x32_bf16 v[34:37], v[238:241], v[206:209], v[34:37]
	v_mfma_f32_16x16x32_bf16 v[22:25], v[230:233], v[214:217], v[22:25]
	v_mfma_f32_16x16x32_bf16 v[18:21], v[238:241], v[214:217], v[18:21]
	v_mfma_f32_16x16x32_bf16 v[6:9], v[230:233], v[222:225], v[6:9]
	v_mfma_f32_16x16x32_bf16 v[2:5], v[238:241], v[222:225], v[2:5]
	s_setprio 0
	s_add_i32 s43, s97, 0x100
	v_add_u32_e32 v0, s43, v151
	s_barrier
	ds_read_b128 v[154:157], v0
	ds_read_b128 v[170:173], v0 offset:1024
	ds_read_b128 v[174:177], v0 offset:2048
	ds_read_b128 v[178:181], v0 offset:3072
	s_add_u32 s28, s62, 0x40000
	s_addc_u32 s29, s63, 0
	s_mov_b32 m0, s11
	v_lshl_add_u64 v[226:227], s[28:29], 0, v[130:131]
	ds_read_b128 v[182:185], v168 offset:32768
	ds_read_b128 v[186:189], v168 offset:33792
	ds_read_b128 v[190:193], v168 offset:34816
	ds_read_b128 v[206:209], v168 offset:35840
	ds_read_b128 v[210:213], v168 offset:36864
	ds_read_b128 v[214:217], v168 offset:37888
	ds_read_b128 v[218:221], v168 offset:38912
	ds_read_b128 v[222:225], v168 offset:39936
	global_load_lds_dwordx4 v[226:227], off
	v_lshl_add_u64 v[226:227], s[28:29], 0, v[134:135]
	s_mov_b32 m0, s12
	s_nop 0
	global_load_lds_dwordx4 v[226:227], off
	s_waitcnt lgkmcnt(8)
	s_barrier
	s_waitcnt lgkmcnt(0)
	s_setprio 1
	s_waitcnt lgkmcnt(0)
	v_mfma_f32_16x16x32_bf16 v[126:129], v[154:157], v[182:185], v[126:129]
	v_mfma_f32_16x16x32_bf16 v[122:125], v[174:177], v[182:185], v[122:125]
	v_mfma_f32_16x16x32_bf16 v[110:113], v[154:157], v[190:193], v[110:113]
	v_mfma_f32_16x16x32_bf16 v[106:109], v[174:177], v[190:193], v[106:109]
	v_mfma_f32_16x16x32_bf16 v[94:97], v[154:157], v[210:213], v[94:97]
	v_mfma_f32_16x16x32_bf16 v[90:93], v[174:177], v[210:213], v[90:93]
	v_mfma_f32_16x16x32_bf16 v[78:81], v[154:157], v[218:221], v[78:81]
	v_mfma_f32_16x16x32_bf16 v[74:77], v[174:177], v[218:221], v[74:77]
	v_mfma_f32_16x16x32_bf16 v[126:129], v[170:173], v[186:189], v[126:129]
	v_mfma_f32_16x16x32_bf16 v[122:125], v[178:181], v[186:189], v[122:125]
	v_mfma_f32_16x16x32_bf16 v[110:113], v[170:173], v[206:209], v[110:113]
	v_mfma_f32_16x16x32_bf16 v[106:109], v[178:181], v[206:209], v[106:109]
	v_mfma_f32_16x16x32_bf16 v[94:97], v[170:173], v[214:217], v[94:97]
	v_mfma_f32_16x16x32_bf16 v[90:93], v[178:181], v[214:217], v[90:93]
	v_mfma_f32_16x16x32_bf16 v[78:81], v[170:173], v[222:225], v[78:81]
	v_mfma_f32_16x16x32_bf16 v[74:77], v[178:181], v[222:225], v[74:77]
	s_setprio 0
	s_barrier
	s_add_i32 s28, s44, 0x100
	s_add_i32 s29, s43, s8
	v_add_u32_e32 v0, s28, v151
	v_lshl_add_u64 v[158:159], v[158:159], 0, s[46:47]
	s_mov_b32 m0, s29
	ds_read_b128 v[226:229], v0
	ds_read_b128 v[230:233], v0 offset:1024
	ds_read_b128 v[234:237], v0 offset:2048
	ds_read_b128 v[238:241], v0 offset:3072
	global_load_lds_dwordx4 v[158:159], off
	v_lshl_add_u64 v[158:159], v[242:243], 0, s[46:47]
	s_add_i32 m0, s29, 0x2000
	s_nop 0
	global_load_lds_dwordx4 v[158:159], off
	s_barrier
	s_waitcnt lgkmcnt(0)
	s_setprio 1
	s_waitcnt lgkmcnt(0)
	v_mfma_f32_16x16x32_bf16 v[118:121], v[226:229], v[182:185], v[118:121]
	v_mfma_f32_16x16x32_bf16 v[114:117], v[234:237], v[182:185], v[114:117]
	v_mfma_f32_16x16x32_bf16 v[102:105], v[226:229], v[190:193], v[102:105]
	v_mfma_f32_16x16x32_bf16 v[98:101], v[234:237], v[190:193], v[98:101]
	v_mfma_f32_16x16x32_bf16 v[86:89], v[226:229], v[210:213], v[86:89]
	v_mfma_f32_16x16x32_bf16 v[82:85], v[234:237], v[210:213], v[82:85]
	v_mfma_f32_16x16x32_bf16 v[70:73], v[226:229], v[218:221], v[70:73]
	v_mfma_f32_16x16x32_bf16 v[66:69], v[234:237], v[218:221], v[66:69]
	v_mfma_f32_16x16x32_bf16 v[118:121], v[230:233], v[186:189], v[118:121]
	v_mfma_f32_16x16x32_bf16 v[114:117], v[238:241], v[186:189], v[114:117]
	v_mfma_f32_16x16x32_bf16 v[102:105], v[230:233], v[206:209], v[102:105]
	v_mfma_f32_16x16x32_bf16 v[98:101], v[238:241], v[206:209], v[98:101]
	v_mfma_f32_16x16x32_bf16 v[86:89], v[230:233], v[214:217], v[86:89]
	v_mfma_f32_16x16x32_bf16 v[82:85], v[238:241], v[214:217], v[82:85]
	v_mfma_f32_16x16x32_bf16 v[70:73], v[230:233], v[222:225], v[70:73]
	v_mfma_f32_16x16x32_bf16 v[66:69], v[238:241], v[222:225], v[66:69]
	s_setprio 0
	s_mov_b32 m0, s20
	v_lshl_add_u64 v[158:159], v[244:245], 0, s[46:47]
	s_barrier
	ds_read_b128 v[182:185], v168 offset:49152
	ds_read_b128 v[186:189], v168 offset:50176
	ds_read_b128 v[190:193], v168 offset:51200
	ds_read_b128 v[206:209], v168 offset:52224
	ds_read_b128 v[210:213], v168 offset:53248
	ds_read_b128 v[214:217], v168 offset:54272
	ds_read_b128 v[218:221], v168 offset:55296
	ds_read_b128 v[222:225], v168 offset:56320
	global_load_lds_dwordx4 v[158:159], off
	v_lshl_add_u64 v[158:159], v[246:247], 0, s[46:47]
	s_mov_b32 m0, s21
	s_nop 0
	global_load_lds_dwordx4 v[158:159], off
	s_barrier
	s_waitcnt lgkmcnt(0)
	s_setprio 1
	s_waitcnt lgkmcnt(0)
	v_mfma_f32_16x16x32_bf16 v[62:65], v[154:157], v[182:185], v[62:65]
	v_mfma_f32_16x16x32_bf16 v[58:61], v[174:177], v[182:185], v[58:61]
	v_mfma_f32_16x16x32_bf16 v[46:49], v[154:157], v[190:193], v[46:49]
	v_mfma_f32_16x16x32_bf16 v[42:45], v[174:177], v[190:193], v[42:45]
	v_mfma_f32_16x16x32_bf16 v[30:33], v[154:157], v[210:213], v[30:33]
	v_mfma_f32_16x16x32_bf16 v[26:29], v[174:177], v[210:213], v[26:29]
	v_mfma_f32_16x16x32_bf16 v[14:17], v[154:157], v[218:221], v[14:17]
	v_mfma_f32_16x16x32_bf16 v[10:13], v[174:177], v[218:221], v[10:13]
	v_mfma_f32_16x16x32_bf16 v[62:65], v[170:173], v[186:189], v[62:65]
	v_mfma_f32_16x16x32_bf16 v[58:61], v[178:181], v[186:189], v[58:61]
	v_mfma_f32_16x16x32_bf16 v[46:49], v[170:173], v[206:209], v[46:49]
	v_mfma_f32_16x16x32_bf16 v[42:45], v[178:181], v[206:209], v[42:45]
	v_mfma_f32_16x16x32_bf16 v[30:33], v[170:173], v[214:217], v[30:33]
	v_mfma_f32_16x16x32_bf16 v[26:29], v[178:181], v[214:217], v[26:29]
	v_mfma_f32_16x16x32_bf16 v[14:17], v[170:173], v[222:225], v[14:17]
	v_mfma_f32_16x16x32_bf16 v[10:13], v[178:181], v[222:225], v[10:13]
	s_setprio 0
	s_barrier
	s_add_u32 s0, s0, 0x40080
	s_addc_u32 s1, s1, 0
	s_add_i32 s28, s28, s8
	v_lshl_add_u64 v[154:155], s[0:1], 0, v[132:133]
	s_mov_b32 m0, s28
	s_nop 0
	global_load_lds_dwordx4 v[154:155], off
	v_lshl_add_u64 v[154:155], s[0:1], 0, v[136:137]
	s_add_i32 m0, s28, 0x2000
	s_nop 0
	global_load_lds_dwordx4 v[154:155], off
	s_waitcnt vmcnt(6)
	s_barrier
	s_setprio 1
	v_mfma_f32_16x16x32_bf16 v[54:57], v[226:229], v[182:185], v[54:57]
	v_mfma_f32_16x16x32_bf16 v[50:53], v[234:237], v[182:185], v[50:53]
	v_mfma_f32_16x16x32_bf16 v[38:41], v[226:229], v[190:193], v[38:41]
	v_mfma_f32_16x16x32_bf16 v[34:37], v[234:237], v[190:193], v[34:37]
	v_mfma_f32_16x16x32_bf16 v[22:25], v[226:229], v[210:213], v[22:25]
	v_mfma_f32_16x16x32_bf16 v[18:21], v[234:237], v[210:213], v[18:21]
	v_mfma_f32_16x16x32_bf16 v[6:9], v[226:229], v[218:221], v[6:9]
	v_mfma_f32_16x16x32_bf16 v[2:5], v[234:237], v[218:221], v[2:5]
	v_mfma_f32_16x16x32_bf16 v[54:57], v[230:233], v[186:189], v[54:57]
	v_mfma_f32_16x16x32_bf16 v[50:53], v[238:241], v[186:189], v[50:53]
	v_mfma_f32_16x16x32_bf16 v[38:41], v[230:233], v[206:209], v[38:41]
	v_mfma_f32_16x16x32_bf16 v[34:37], v[238:241], v[206:209], v[34:37]
	v_mfma_f32_16x16x32_bf16 v[22:25], v[230:233], v[214:217], v[22:25]
	v_mfma_f32_16x16x32_bf16 v[18:21], v[238:241], v[214:217], v[18:21]
	v_mfma_f32_16x16x32_bf16 v[6:9], v[230:233], v[222:225], v[6:9]
	v_mfma_f32_16x16x32_bf16 v[2:5], v[238:241], v[222:225], v[2:5]
	s_setprio 0
	s_add_i32 s42, s42, 2
	s_add_u32 vcc_lo, vcc_lo, 0x100
	s_addc_u32 vcc_hi, vcc_hi, 0
	s_add_u32 s26, s26, 0x100
	s_addc_u32 s27, s27, 0
	s_cmp_gt_u32 s42, 13
	s_barrier
	s_cbranch_scc1 .Lmy_kexit2

.Lmy_kexit2:
	s_ashr_i32 s5, s58, 1
	s_cmp_lt_i32 s5, 2
	s_cbranch_scc1 .LBB0_894
	s_cmp_eq_u32 s5, 2
	s_mov_b64 s[0:1], -1
	s_cbranch_scc0 .LBB0_893
	s_mov_b64 s[0:1], 0
